# q|k|v projection epilogue: per-head norm gain vectors loaded once per tile instead of 32 load+wait pairs
# speedup vs baseline: 1.0381x; 1.0025x over previous
;     __device__ __forceinline__ void operator()(const f32x4 (&acc)[2][2][4][2], const Unit& u, int wr, int wc, int fr, int fq) const {
;     ...
; #pragma unroll
;         for (int ai = 0; ai < 2; ++ai)
; #pragma unroll
;             for (int m = 0; m < 4; ++m) {
;                 const unsigned off = off0 + (unsigned)(ai * HALF + m * 16) * ldb;
;                 float rstd = 1.0f;
;                 if (!isv) {
;                     float ss = 0.f;
; #pragma unroll
;                     for (int n = 0; n < 2; ++n) { const f32x4 p = acc[ai][0][m][n], q = acc[ai][1][m][n];
;                         ss += ((p[0] * p[0] + p[1] * p[1]) + (p[2] * p[2] + p[3] * p[3])) + ((q[0] * q[0] + q[1] * q[1]) + (q[2] * q[2] + q[3] * q[3])); }
;                     ss += __shfl_xor(ss, 16); ss += __shfl_xor(ss, 32);
;                     rstd = __builtin_amdgcn_rsqf(ss * (1.f / 64.f) + EPS);
;                 }
;                 int frl = fr; asm volatile("" : "+v"(frl));
;                 const int t = (u.pm * BM + ai * HALF + wr * 64 + m * 16 + frl) & (SEQ - 1);
; #pragma unroll
;                 for (int n = 0; n < 2; ++n) {
;                     f32x4 x1 = acc[ai][0][m][n], x2 = acc[ai][1][m][n];
;                     if (!isv) {
;                         x1 = x1 * rstd * *(const f32x4*)(gp + 32 * n + 4 * fq); x2 = x2 * rstd * *(const f32x4*)(gp + 32 * n + 4 * fq + 16);
;                         if (lat) { const float pos = n ? (float)(t & 63) : (float)(t >> 6);
; #pragma unroll
;                             for (int j = 0; j < 4; ++j) { float tr = pos * inv[j]; tr -= rintf(tr);
;                                 const float sn = __builtin_amdgcn_sinf(tr), cs = __builtin_amdgcn_cosf(tr);
;                                 const float a1 = x1[j], a2 = x2[j]; x1[j] = a1 * cs - a2 * sn; x2[j] = a1 * sn + a2 * cs; } }
;                         x1 = x1 * osc; x2 = x2 * osc;
.LBB0_951:
	s_lshl_b32 s0, s6, 8
	s_cmp_lt_i32 s6, 64
	s_cselect_b64 s[6:7], -1, 0
	s_cmp_lt_i32 s40, 4
	s_cselect_b64 vcc, -1, 0
	s_and_b64 s[8:9], vcc, exec
	v_mov_b32_e32 v142, 0x3e38aa3b
	s_cselect_b32 s9, s13, s15
	s_cselect_b32 s8, s12, s14
	v_cndmask_b32_e64 v150, 0, 1, s[22:23]
	v_cndmask_b32_e32 v142, 1.0, v142, vcc
	v_lshl_add_u64 v[146:147], s[8:9], 0, v[96:97]
	v_cmp_ne_u32_e64 s[8:9], 1, v150
	v_cndmask_b32_e64 v150, 0, 1, s[6:7]
	s_add_i32 s24, s0, s85
	v_mov_b32_e32 v143, v142
	v_mov_b32_e32 v145, v152
	v_mov_b32_e32 v149, v148
	s_andn2_b64 vcc, exec, s[22:23]
	v_cmp_ne_u32_e64 s[6:7], 1, v150
	s_cbranch_vccnz .LBB0_955
	v_mov_b32_e32 v150, v148
	v_mov_b32_e32 v151, v148
	v_pk_mul_f32 v[160:161], v[128:129], v[150:151]
	v_pk_mul_f32 v[162:163], v[126:127], v[148:149]
	global_load_dwordx4 v[226:229], v[146:147], off
	global_load_dwordx4 v[230:233], v[146:147], off offset:64
	global_load_dwordx4 v[234:237], v[146:147], off offset:128
	global_load_dwordx4 v[238:241], v[146:147], off offset:192
	s_waitcnt vmcnt(0)
	v_mov_b64_e32 v[126:127], v[226:227]
	v_mov_b64_e32 v[128:129], v[228:229]
	v_pk_mul_f32 v[124:125], v[124:125], v[150:151]
	v_pk_mul_f32 v[150:151], v[122:123], v[148:149]
	s_and_b64 vcc, exec, s[6:7]
	v_pk_mul_f32 v[128:129], v[160:161], v[128:129]
	v_pk_mul_f32 v[126:127], v[162:163], v[126:127]
	v_mov_b64_e32 v[160:161], v[230:231]
	v_mov_b64_e32 v[162:163], v[232:233]
	v_pk_mul_f32 v[122:123], v[124:125], v[162:163]
	v_pk_mul_f32 v[150:151], v[150:151], v[160:161]
	s_cbranch_vccnz .LBB0_954
	v_add_u32_e32 v124, s24, v145
	v_bfe_u32 v124, v124, 6, 5
	v_cvt_f32_ubyte0_e32 v165, v124
	v_mul_f32_e32 v124, v155, v165
	v_rndne_f32_e32 v124, v124
	v_fma_f32 v125, v155, v165, -v124
	v_sin_f32_e32 v124, v125
	v_cos_f32_e32 v160, v125
	v_mul_f32_e32 v125, v156, v165
	v_rndne_f32_e32 v125, v125
	v_mul_f32_e32 v162, v157, v165
	v_mul_f32_e32 v168, v158, v165
	v_fma_f32 v161, v156, v165, -v125
	v_rndne_f32_e32 v162, v162
	v_rndne_f32_e32 v168, v168
	v_sin_f32_e32 v125, v161
	v_fma_f32 v162, v157, v165, -v162
	v_fma_f32 v165, v158, v165, -v168
	v_cos_f32_e32 v161, v161
	v_cos_f32_e32 v167, v162
	v_sin_f32_e32 v170, v162
	v_sin_f32_e32 v169, v165
	v_cos_f32_e32 v168, v165
	v_pk_mul_f32 v[162:163], v[124:125], v[150:151]
	v_pk_mul_f32 v[150:151], v[160:161], v[150:151]
	v_mul_f32_e32 v166, v170, v122
	v_mul_f32_e32 v172, v167, v122
	v_mov_b32_e32 v122, v129
	v_pk_fma_f32 v[160:161], v[160:161], v[126:127], v[162:163] neg_lo:[0,0,1] neg_hi:[0,0,1]
	v_mov_b32_e32 v162, v169
	v_mov_b32_e32 v163, v168
	v_mul_f32_e32 v164, v167, v128
	v_mul_f32_e32 v170, v170, v128
	v_pk_mul_f32 v[128:129], v[168:169], v[122:123]
	v_pk_mul_f32 v[122:123], v[162:163], v[122:123]
	v_mov_b32_e32 v165, v128
	v_mov_b32_e32 v167, v129
	v_mov_b32_e32 v171, v122
	v_mov_b32_e32 v173, v123
	v_pk_add_f32 v[128:129], v[164:165], v[166:167] neg_lo:[0,1] neg_hi:[0,1]
	v_pk_fma_f32 v[150:151], v[124:125], v[126:127], v[150:151]
	v_pk_add_f32 v[122:123], v[170:171], v[172:173]
	v_mov_b32_e32 v126, v160
	v_mov_b32_e32 v127, v161

; __device__ __forceinline__ unsigned cvt_pk_bf16(float lo, float hi) { unsigned r; asm volatile("v_cvt_pk_bf16_f32 %0, %1, %2" : "=v"(r) : "v"(lo), "v"(hi)); return r; }
;     __device__ __forceinline__ void operator()(const f32x4 (&acc)[2][2][4][2], const Unit& u, int wr, int wc, int fr, int fq) const {
;     ...
; #pragma unroll
;                 for (int n = 0; n < 2; ++n) {
;                     f32x4 x1 = acc[ai][0][m][n], x2 = acc[ai][1][m][n];
;                     if (!isv) {
;                         x1 = x1 * rstd * *(const f32x4*)(gp + 32 * n + 4 * fq); x2 = x2 * rstd * *(const f32x4*)(gp + 32 * n + 4 * fq + 16);
;                         if (lat) { const float pos = n ? (float)(t & 63) : (float)(t >> 6);
; #pragma unroll
;                             for (int j = 0; j < 4; ++j) { float tr = pos * inv[j]; tr -= rintf(tr);
;                                 const float sn = __builtin_amdgcn_sinf(tr), cs = __builtin_amdgcn_cosf(tr);
;                                 const float a1 = x1[j], a2 = x2[j]; x1[j] = a1 * cs - a2 * sn; x2[j] = a1 * sn + a2 * cs; } }
;                         x1 = x1 * osc; x2 = x2 * osc;
;                     }
;                     u32x2 a1, a2; a1.x = cvt_pk_bf16(x1[0], x1[1]); a1.y = cvt_pk_bf16(x1[2], x1[3]); a2.x = cvt_pk_bf16(x2[0], x2[1]); a2.y = cvt_pk_bf16(x2[2], x2[3]);
;                     *(u32x2*)(base + off + n * 64) = a1; *(u32x2*)(base + off + n * 64 + 32) = a2; }
.LBB0_955:
	s_mul_hi_i32 s3, s0, 0xc00
	s_mul_i32 s22, s0, 0xc00
	s_lshl_b32 s0, s40, 8
	s_ashr_i32 s1, s0, 31
	v_readlane_b32 s36, v254, 37
	v_readlane_b32 s37, v254, 38
	s_add_u32 s22, s36, s22
	s_addc_u32 s3, s37, s3
	s_lshl_b64 s[0:1], s[0:1], 1
	s_add_u32 s0, s22, s0
	s_addc_u32 s1, s3, s1
	s_add_u32 s60, s0, s92
	s_addc_u32 s61, s1, 0
	s_and_b64 vcc, exec, s[8:9]
	v_cvt_pk_bf16_f32 v126, v126, v127
	v_cvt_pk_bf16_f32 v127, v128, v129
	v_cvt_pk_bf16_f32 v122, v122, v123
	v_cvt_pk_bf16_f32 v123, v124, v125
	global_store_dwordx2 v144, v[126:127], s[60:61]
	global_store_dwordx2 v144, v[122:123], s[60:61] offset:32
	s_cbranch_vccnz .LBB0_959
	v_mov_b32_e32 v122, v148
	v_mov_b32_e32 v123, v148
	v_pk_mul_f32 v[124:125], v[120:121], v[122:123]
	v_pk_mul_f32 v[126:127], v[118:119], v[148:149]
	v_mov_b64_e32 v[118:119], v[234:235]
	v_mov_b64_e32 v[120:121], v[236:237]
	v_pk_mul_f32 v[116:117], v[116:117], v[122:123]
	s_and_b64 vcc, exec, s[6:7]
	v_pk_mul_f32 v[120:121], v[124:125], v[120:121]
	v_mov_b64_e32 v[122:123], v[238:239]
	v_mov_b64_e32 v[124:125], v[240:241]
	v_pk_mul_f32 v[118:119], v[126:127], v[118:119]
	v_pk_mul_f32 v[126:127], v[114:115], v[148:149]
	v_pk_mul_f32 v[114:115], v[116:117], v[124:125]
	v_pk_mul_f32 v[122:123], v[126:127], v[122:123]
	s_cbranch_vccnz .LBB0_958
	v_and_b32_e32 v116, 63, v145
	v_cvt_f32_ubyte0_e32 v129, v116
	v_mul_f32_e32 v116, v155, v129
	v_rndne_f32_e32 v116, v116
	v_fma_f32 v117, v155, v129, -v116
	v_sin_f32_e32 v116, v117
	v_cos_f32_e32 v124, v117
	v_mul_f32_e32 v117, v156, v129
	v_rndne_f32_e32 v117, v117
	v_mul_f32_e32 v126, v157, v129
	v_mul_f32_e32 v150, v158, v129
	v_fma_f32 v125, v156, v129, -v117
	v_rndne_f32_e32 v126, v126
	v_rndne_f32_e32 v150, v150
	v_sin_f32_e32 v117, v125
	v_fma_f32 v126, v157, v129, -v126
	v_fma_f32 v129, v158, v129, -v150
	v_cos_f32_e32 v125, v125
	v_cos_f32_e32 v145, v126
	v_sin_f32_e32 v149, v126
	v_sin_f32_e32 v151, v129
	v_cos_f32_e32 v150, v129
	v_pk_mul_f32 v[126:127], v[116:117], v[122:123]
	v_pk_mul_f32 v[122:123], v[124:125], v[122:123]
	v_mul_f32_e32 v148, v149, v114
	v_mul_f32_e32 v162, v145, v114
	v_mov_b32_e32 v114, v121
	v_pk_fma_f32 v[124:125], v[124:125], v[118:119], v[126:127] neg_lo:[0,0,1] neg_hi:[0,0,1]
	v_mov_b32_e32 v126, v151
	v_mov_b32_e32 v127, v150
	v_mul_f32_e32 v128, v145, v120
	v_mul_f32_e32 v160, v149, v120
	v_pk_mul_f32 v[120:121], v[150:151], v[114:115]
	v_pk_mul_f32 v[114:115], v[126:127], v[114:115]
	v_mov_b32_e32 v129, v120
	v_mov_b32_e32 v149, v121
	v_mov_b32_e32 v161, v114
	v_mov_b32_e32 v163, v115
	v_pk_add_f32 v[120:121], v[128:129], v[148:149] neg_lo:[0,1] neg_hi:[0,1]
	v_pk_fma_f32 v[122:123], v[116:117], v[118:119], v[122:123]
	v_pk_add_f32 v[114:115], v[160:161], v[162:163]
	v_mov_b32_e32 v118, v124
	v_mov_b32_e32 v119, v125

;     __device__ __forceinline__ void operator()(const f32x4 (&acc)[2][2][4][2], const Unit& u, int wr, int wc, int fr, int fq) const {
;     ...
;                 int frl = fr; asm volatile("" : "+v"(frl));
;                 const int t = (u.pm * BM + ai * HALF + wr * 64 + m * 16 + frl) & (SEQ - 1);
; #pragma unroll
;                 for (int n = 0; n < 2; ++n) {
;                     f32x4 x1 = acc[ai][0][m][n], x2 = acc[ai][1][m][n];
;                     if (!isv) {
;                         x1 = x1 * rstd * *(const f32x4*)(gp + 32 * n + 4 * fq); x2 = x2 * rstd * *(const f32x4*)(gp + 32 * n + 4 * fq + 16);
;                         if (lat) { const float pos = n ? (float)(t & 63) : (float)(t >> 6);
; #pragma unroll
;                             for (int j = 0; j < 4; ++j) { float tr = pos * inv[j]; tr -= rintf(tr);
;                                 const float sn = __builtin_amdgcn_sinf(tr), cs = __builtin_amdgcn_cosf(tr);
;                                 const float a1 = x1[j], a2 = x2[j]; x1[j] = a1 * cs - a2 * sn; x2[j] = a1 * sn + a2 * cs; } }
;                         x1 = x1 * osc; x2 = x2 * osc;
.LBB0_961:
	v_mov_b32_e32 v115, v152
	s_and_b64 vcc, exec, s[8:9]
	v_add3_u32 v118, v115, s24, 16
	v_mov_b32_e32 v115, v114
	s_cbranch_vccnz .LBB0_965
	v_mov_b32_e32 v116, v114
	v_mov_b32_e32 v117, v114
	v_pk_mul_f32 v[120:121], v[112:113], v[116:117]
	v_pk_mul_f32 v[122:123], v[110:111], v[114:115]
	v_mov_b64_e32 v[110:111], v[226:227]
	v_mov_b64_e32 v[112:113], v[228:229]
	v_pk_mul_f32 v[108:109], v[108:109], v[116:117]
	v_pk_mul_f32 v[116:117], v[106:107], v[114:115]
	s_and_b64 vcc, exec, s[6:7]
	v_pk_mul_f32 v[112:113], v[120:121], v[112:113]
	v_pk_mul_f32 v[110:111], v[122:123], v[110:111]
	v_mov_b64_e32 v[120:121], v[230:231]
	v_mov_b64_e32 v[122:123], v[232:233]
	v_pk_mul_f32 v[106:107], v[108:109], v[122:123]
	v_pk_mul_f32 v[116:117], v[116:117], v[120:121]
	s_cbranch_vccnz .LBB0_964
	v_bfe_u32 v108, v118, 6, 5
	v_cvt_f32_ubyte0_e32 v119, v108
	v_mul_f32_e32 v108, v155, v119
	v_rndne_f32_e32 v108, v108
	v_fma_f32 v109, v155, v119, -v108
	v_sin_f32_e32 v108, v109
	v_cos_f32_e32 v120, v109
	v_mul_f32_e32 v109, v156, v119
	v_rndne_f32_e32 v109, v109
	v_mul_f32_e32 v122, v157, v119
	v_mul_f32_e32 v128, v158, v119
	v_fma_f32 v121, v156, v119, -v109
	v_rndne_f32_e32 v122, v122
	v_rndne_f32_e32 v128, v128
	v_sin_f32_e32 v109, v121
	v_fma_f32 v122, v157, v119, -v122
	v_fma_f32 v119, v158, v119, -v128
	v_cos_f32_e32 v121, v121
	v_cos_f32_e32 v125, v122
	v_sin_f32_e32 v127, v122
	v_sin_f32_e32 v129, v119
	v_cos_f32_e32 v128, v119
	v_pk_mul_f32 v[122:123], v[108:109], v[116:117]
	v_pk_mul_f32 v[116:117], v[120:121], v[116:117]
	v_mul_f32_e32 v126, v127, v106
	v_mul_f32_e32 v150, v125, v106
	v_mov_b32_e32 v106, v113
	v_pk_fma_f32 v[120:121], v[120:121], v[110:111], v[122:123] neg_lo:[0,0,1] neg_hi:[0,0,1]
	v_mov_b32_e32 v122, v129
	v_mov_b32_e32 v123, v128
	v_mul_f32_e32 v124, v125, v112
	v_mul_f32_e32 v148, v127, v112
	v_pk_mul_f32 v[112:113], v[128:129], v[106:107]
	v_pk_mul_f32 v[106:107], v[122:123], v[106:107]
	v_mov_b32_e32 v125, v112
	v_mov_b32_e32 v127, v113
	v_mov_b32_e32 v149, v106
	v_mov_b32_e32 v151, v107
	v_pk_add_f32 v[112:113], v[124:125], v[126:127] neg_lo:[0,1] neg_hi:[0,1]
	v_pk_fma_f32 v[116:117], v[108:109], v[110:111], v[116:117]
	v_pk_add_f32 v[106:107], v[148:149], v[150:151]
	v_mov_b32_e32 v110, v120
	v_mov_b32_e32 v111, v121

; __device__ __forceinline__ unsigned cvt_pk_bf16(float lo, float hi) { unsigned r; asm volatile("v_cvt_pk_bf16_f32 %0, %1, %2" : "=v"(r) : "v"(lo), "v"(hi)); return r; }
;     __device__ __forceinline__ void operator()(const f32x4 (&acc)[2][2][4][2], const Unit& u, int wr, int wc, int fr, int fq) const {
;     ...
; #pragma unroll
;                 for (int n = 0; n < 2; ++n) {
;                     f32x4 x1 = acc[ai][0][m][n], x2 = acc[ai][1][m][n];
;                     if (!isv) {
;                         x1 = x1 * rstd * *(const f32x4*)(gp + 32 * n + 4 * fq); x2 = x2 * rstd * *(const f32x4*)(gp + 32 * n + 4 * fq + 16);
;                         if (lat) { const float pos = n ? (float)(t & 63) : (float)(t >> 6);
; #pragma unroll
;                             for (int j = 0; j < 4; ++j) { float tr = pos * inv[j]; tr -= rintf(tr);
;                                 const float sn = __builtin_amdgcn_sinf(tr), cs = __builtin_amdgcn_cosf(tr);
;                                 const float a1 = x1[j], a2 = x2[j]; x1[j] = a1 * cs - a2 * sn; x2[j] = a1 * sn + a2 * cs; } }
;                         x1 = x1 * osc; x2 = x2 * osc;
;                     }
;                     u32x2 a1, a2; a1.x = cvt_pk_bf16(x1[0], x1[1]); a1.y = cvt_pk_bf16(x1[2], x1[3]); a2.x = cvt_pk_bf16(x2[0], x2[1]); a2.y = cvt_pk_bf16(x2[2], x2[3]);
;                     *(u32x2*)(base + off + n * 64) = a1; *(u32x2*)(base + off + n * 64 + 32) = a2; }
.LBB0_965:
	v_add_u32_e32 v116, 0xc000, v144
	s_and_b64 vcc, exec, s[8:9]
	v_cvt_pk_bf16_f32 v110, v110, v111
	v_cvt_pk_bf16_f32 v111, v112, v113
	v_cvt_pk_bf16_f32 v106, v106, v107
	v_cvt_pk_bf16_f32 v107, v108, v109
	global_store_dwordx2 v116, v[110:111], s[60:61]
	global_store_dwordx2 v116, v[106:107], s[60:61] offset:32
	s_cbranch_vccnz .LBB0_969
	v_mov_b32_e32 v106, v114
	v_mov_b32_e32 v107, v114
	v_pk_mul_f32 v[108:109], v[104:105], v[106:107]
	v_pk_mul_f32 v[110:111], v[102:103], v[114:115]
	v_mov_b64_e32 v[102:103], v[234:235]
	v_mov_b64_e32 v[104:105], v[236:237]
	v_pk_mul_f32 v[100:101], v[100:101], v[106:107]
	s_and_b64 vcc, exec, s[6:7]
	v_pk_mul_f32 v[104:105], v[108:109], v[104:105]
	v_mov_b64_e32 v[106:107], v[238:239]
	v_mov_b64_e32 v[108:109], v[240:241]
	v_pk_mul_f32 v[102:103], v[110:111], v[102:103]
	v_pk_mul_f32 v[110:111], v[98:99], v[114:115]
	v_pk_mul_f32 v[98:99], v[100:101], v[108:109]
	v_pk_mul_f32 v[106:107], v[110:111], v[106:107]
	s_cbranch_vccnz .LBB0_968
	v_and_b32_e32 v100, 63, v118
	v_cvt_f32_ubyte0_e32 v113, v100
	v_mul_f32_e32 v100, v155, v113
	v_rndne_f32_e32 v100, v100
	v_fma_f32 v101, v155, v113, -v100
	v_sin_f32_e32 v100, v101
	v_cos_f32_e32 v108, v101
	v_mul_f32_e32 v101, v156, v113
	v_rndne_f32_e32 v101, v101
	v_mul_f32_e32 v110, v157, v113
	v_mul_f32_e32 v118, v158, v113
	v_fma_f32 v109, v156, v113, -v101
	v_rndne_f32_e32 v110, v110
	v_rndne_f32_e32 v118, v118
	v_sin_f32_e32 v101, v109
	v_fma_f32 v110, v157, v113, -v110
	v_fma_f32 v113, v158, v113, -v118
	v_cos_f32_e32 v109, v109
	v_cos_f32_e32 v115, v110
	v_sin_f32_e32 v117, v110
	v_sin_f32_e32 v119, v113
	v_cos_f32_e32 v118, v113
	v_pk_mul_f32 v[110:111], v[100:101], v[106:107]
	v_pk_mul_f32 v[106:107], v[108:109], v[106:107]
	v_mul_f32_e32 v114, v117, v98
	v_mul_f32_e32 v122, v115, v98
	v_mov_b32_e32 v98, v105
	v_pk_fma_f32 v[108:109], v[108:109], v[102:103], v[110:111] neg_lo:[0,0,1] neg_hi:[0,0,1]
	v_mov_b32_e32 v110, v119
	v_mov_b32_e32 v111, v118
	v_mul_f32_e32 v112, v115, v104
	v_mul_f32_e32 v120, v117, v104
	v_pk_mul_f32 v[104:105], v[118:119], v[98:99]
	v_pk_mul_f32 v[98:99], v[110:111], v[98:99]
	v_mov_b32_e32 v113, v104
	v_mov_b32_e32 v115, v105
	v_mov_b32_e32 v121, v98
	v_mov_b32_e32 v123, v99
	v_pk_add_f32 v[104:105], v[112:113], v[114:115] neg_lo:[0,1] neg_hi:[0,1]
	v_pk_fma_f32 v[106:107], v[100:101], v[102:103], v[106:107]
	v_pk_add_f32 v[98:99], v[120:121], v[122:123]
	v_mov_b32_e32 v102, v108
	v_mov_b32_e32 v103, v109

;     __device__ __forceinline__ void operator()(const f32x4 (&acc)[2][2][4][2], const Unit& u, int wr, int wc, int fr, int fq) const {
;     ...
;                 int frl = fr; asm volatile("" : "+v"(frl));
;                 const int t = (u.pm * BM + ai * HALF + wr * 64 + m * 16 + frl) & (SEQ - 1);
; #pragma unroll
;                 for (int n = 0; n < 2; ++n) {
;                     f32x4 x1 = acc[ai][0][m][n], x2 = acc[ai][1][m][n];
;                     if (!isv) {
;                         x1 = x1 * rstd * *(const f32x4*)(gp + 32 * n + 4 * fq); x2 = x2 * rstd * *(const f32x4*)(gp + 32 * n + 4 * fq + 16);
;                         if (lat) { const float pos = n ? (float)(t & 63) : (float)(t >> 6);
; #pragma unroll
;                             for (int j = 0; j < 4; ++j) { float tr = pos * inv[j]; tr -= rintf(tr);
;                                 const float sn = __builtin_amdgcn_sinf(tr), cs = __builtin_amdgcn_cosf(tr);
;                                 const float a1 = x1[j], a2 = x2[j]; x1[j] = a1 * cs - a2 * sn; x2[j] = a1 * sn + a2 * cs; } }
;                         x1 = x1 * osc; x2 = x2 * osc;
.LBB0_971:
	v_mov_b32_e32 v99, v152
	s_and_b64 vcc, exec, s[8:9]
	v_add3_u32 v102, v99, s24, 32
	v_mov_b32_e32 v99, v98
	s_cbranch_vccnz .LBB0_975
	v_mov_b32_e32 v100, v98
	v_mov_b32_e32 v101, v98
	v_pk_mul_f32 v[104:105], v[94:95], v[100:101]
	v_pk_mul_f32 v[106:107], v[92:93], v[98:99]
	v_mov_b64_e32 v[92:93], v[226:227]
	v_mov_b64_e32 v[94:95], v[228:229]
	v_pk_mul_f32 v[90:91], v[90:91], v[100:101]
	v_pk_mul_f32 v[100:101], v[88:89], v[98:99]
	s_and_b64 vcc, exec, s[6:7]
	v_pk_mul_f32 v[94:95], v[104:105], v[94:95]
	v_pk_mul_f32 v[92:93], v[106:107], v[92:93]
	v_mov_b64_e32 v[104:105], v[230:231]
	v_mov_b64_e32 v[106:107], v[232:233]
	v_pk_mul_f32 v[88:89], v[90:91], v[106:107]
	v_pk_mul_f32 v[100:101], v[100:101], v[104:105]
	s_cbranch_vccnz .LBB0_974
	v_bfe_u32 v90, v102, 6, 5
	v_cvt_f32_ubyte0_e32 v103, v90
	v_mul_f32_e32 v90, v155, v103
	v_rndne_f32_e32 v90, v90
	v_fma_f32 v91, v155, v103, -v90
	v_sin_f32_e32 v90, v91
	v_cos_f32_e32 v104, v91
	v_mul_f32_e32 v91, v156, v103
	v_rndne_f32_e32 v91, v91
	v_mul_f32_e32 v106, v157, v103
	v_mul_f32_e32 v112, v158, v103
	v_fma_f32 v105, v156, v103, -v91
	v_rndne_f32_e32 v106, v106
	v_rndne_f32_e32 v112, v112
	v_sin_f32_e32 v91, v105
	v_fma_f32 v106, v157, v103, -v106
	v_fma_f32 v103, v158, v103, -v112
	v_cos_f32_e32 v105, v105
	v_cos_f32_e32 v109, v106
	v_sin_f32_e32 v111, v106
	v_sin_f32_e32 v113, v103
	v_cos_f32_e32 v112, v103
	v_pk_mul_f32 v[106:107], v[90:91], v[100:101]
	v_pk_mul_f32 v[100:101], v[104:105], v[100:101]
	v_mul_f32_e32 v110, v111, v88
	v_mul_f32_e32 v116, v109, v88
	v_mov_b32_e32 v88, v95
	v_pk_fma_f32 v[104:105], v[104:105], v[92:93], v[106:107] neg_lo:[0,0,1] neg_hi:[0,0,1]
	v_mov_b32_e32 v106, v113
	v_mov_b32_e32 v107, v112
	v_mul_f32_e32 v108, v109, v94
	v_mul_f32_e32 v114, v111, v94
	v_pk_mul_f32 v[94:95], v[112:113], v[88:89]
	v_pk_mul_f32 v[88:89], v[106:107], v[88:89]
	v_mov_b32_e32 v109, v94
	v_mov_b32_e32 v111, v95
	v_mov_b32_e32 v115, v88
	v_mov_b32_e32 v117, v89
	v_pk_add_f32 v[94:95], v[108:109], v[110:111] neg_lo:[0,1] neg_hi:[0,1]
	v_pk_fma_f32 v[100:101], v[90:91], v[92:93], v[100:101]
	v_pk_add_f32 v[88:89], v[114:115], v[116:117]
	v_mov_b32_e32 v92, v104
	v_mov_b32_e32 v93, v105

; __device__ __forceinline__ unsigned cvt_pk_bf16(float lo, float hi) { unsigned r; asm volatile("v_cvt_pk_bf16_f32 %0, %1, %2" : "=v"(r) : "v"(lo), "v"(hi)); return r; }
;     __device__ __forceinline__ void operator()(const f32x4 (&acc)[2][2][4][2], const Unit& u, int wr, int wc, int fr, int fq) const {
;     ...
; #pragma unroll
;                 for (int n = 0; n < 2; ++n) {
;                     f32x4 x1 = acc[ai][0][m][n], x2 = acc[ai][1][m][n];
;                     if (!isv) {
;                         x1 = x1 * rstd * *(const f32x4*)(gp + 32 * n + 4 * fq); x2 = x2 * rstd * *(const f32x4*)(gp + 32 * n + 4 * fq + 16);
;                         if (lat) { const float pos = n ? (float)(t & 63) : (float)(t >> 6);
; #pragma unroll
;                             for (int j = 0; j < 4; ++j) { float tr = pos * inv[j]; tr -= rintf(tr);
;                                 const float sn = __builtin_amdgcn_sinf(tr), cs = __builtin_amdgcn_cosf(tr);
;                                 const float a1 = x1[j], a2 = x2[j]; x1[j] = a1 * cs - a2 * sn; x2[j] = a1 * sn + a2 * cs; } }
;                         x1 = x1 * osc; x2 = x2 * osc;
;                     }
;                     u32x2 a1, a2; a1.x = cvt_pk_bf16(x1[0], x1[1]); a1.y = cvt_pk_bf16(x1[2], x1[3]); a2.x = cvt_pk_bf16(x2[0], x2[1]); a2.y = cvt_pk_bf16(x2[2], x2[3]);
;                     *(u32x2*)(base + off + n * 64) = a1; *(u32x2*)(base + off + n * 64 + 32) = a2; }
.LBB0_975:
	v_add_u32_e32 v100, 0x18000, v144
	s_and_b64 vcc, exec, s[8:9]
	v_cvt_pk_bf16_f32 v92, v92, v93
	v_cvt_pk_bf16_f32 v93, v94, v95
	v_cvt_pk_bf16_f32 v88, v88, v89
	v_cvt_pk_bf16_f32 v89, v90, v91
	global_store_dwordx2 v100, v[92:93], s[60:61]
	global_store_dwordx2 v100, v[88:89], s[60:61] offset:32
	s_cbranch_vccnz .LBB0_979
	v_mov_b32_e32 v88, v98
	v_mov_b32_e32 v89, v98
	v_pk_mul_f32 v[90:91], v[86:87], v[88:89]
	v_pk_mul_f32 v[92:93], v[84:85], v[98:99]
	v_mov_b64_e32 v[84:85], v[234:235]
	v_mov_b64_e32 v[86:87], v[236:237]
	v_pk_mul_f32 v[82:83], v[82:83], v[88:89]
	s_and_b64 vcc, exec, s[6:7]
	v_pk_mul_f32 v[86:87], v[90:91], v[86:87]
	v_mov_b64_e32 v[88:89], v[238:239]
	v_mov_b64_e32 v[90:91], v[240:241]
	v_pk_mul_f32 v[84:85], v[92:93], v[84:85]
	v_pk_mul_f32 v[92:93], v[80:81], v[98:99]
	v_pk_mul_f32 v[80:81], v[82:83], v[90:91]
	v_pk_mul_f32 v[88:89], v[92:93], v[88:89]
	s_cbranch_vccnz .LBB0_978
	v_and_b32_e32 v82, 63, v102
	v_cvt_f32_ubyte0_e32 v95, v82
	v_mul_f32_e32 v82, v155, v95
	v_rndne_f32_e32 v82, v82
	v_fma_f32 v83, v155, v95, -v82
	v_sin_f32_e32 v82, v83
	v_cos_f32_e32 v90, v83
	v_mul_f32_e32 v83, v156, v95
	v_rndne_f32_e32 v83, v83
	v_mul_f32_e32 v92, v157, v95
	v_mul_f32_e32 v102, v158, v95
	v_fma_f32 v91, v156, v95, -v83
	v_rndne_f32_e32 v92, v92
	v_rndne_f32_e32 v102, v102
	v_sin_f32_e32 v83, v91
	v_fma_f32 v92, v157, v95, -v92
	v_fma_f32 v95, v158, v95, -v102
	v_cos_f32_e32 v91, v91
	v_cos_f32_e32 v99, v92
	v_sin_f32_e32 v101, v92
	v_sin_f32_e32 v103, v95
	v_cos_f32_e32 v102, v95
	v_pk_mul_f32 v[92:93], v[82:83], v[88:89]
	v_pk_mul_f32 v[88:89], v[90:91], v[88:89]
	v_mul_f32_e32 v98, v101, v80
	v_mul_f32_e32 v106, v99, v80
	v_mov_b32_e32 v80, v87
	v_pk_fma_f32 v[90:91], v[90:91], v[84:85], v[92:93] neg_lo:[0,0,1] neg_hi:[0,0,1]
	v_mov_b32_e32 v92, v103
	v_mov_b32_e32 v93, v102
	v_mul_f32_e32 v94, v99, v86
	v_mul_f32_e32 v104, v101, v86
	v_pk_mul_f32 v[86:87], v[102:103], v[80:81]
	v_pk_mul_f32 v[80:81], v[92:93], v[80:81]
	v_mov_b32_e32 v95, v86
	v_mov_b32_e32 v99, v87
	v_mov_b32_e32 v105, v80
	v_mov_b32_e32 v107, v81
	v_pk_add_f32 v[86:87], v[94:95], v[98:99] neg_lo:[0,1] neg_hi:[0,1]
	v_pk_fma_f32 v[88:89], v[82:83], v[84:85], v[88:89]
	v_pk_add_f32 v[80:81], v[104:105], v[106:107]
	v_mov_b32_e32 v84, v90
	v_mov_b32_e32 v85, v91

;     __device__ __forceinline__ void operator()(const f32x4 (&acc)[2][2][4][2], const Unit& u, int wr, int wc, int fr, int fq) const {
;     ...
;                 int frl = fr; asm volatile("" : "+v"(frl));
;                 const int t = (u.pm * BM + ai * HALF + wr * 64 + m * 16 + frl) & (SEQ - 1);
; #pragma unroll
;                 for (int n = 0; n < 2; ++n) {
;                     f32x4 x1 = acc[ai][0][m][n], x2 = acc[ai][1][m][n];
;                     if (!isv) {
;                         x1 = x1 * rstd * *(const f32x4*)(gp + 32 * n + 4 * fq); x2 = x2 * rstd * *(const f32x4*)(gp + 32 * n + 4 * fq + 16);
;                         if (lat) { const float pos = n ? (float)(t & 63) : (float)(t >> 6);
; #pragma unroll
;                             for (int j = 0; j < 4; ++j) { float tr = pos * inv[j]; tr -= rintf(tr);
;                                 const float sn = __builtin_amdgcn_sinf(tr), cs = __builtin_amdgcn_cosf(tr);
;                                 const float a1 = x1[j], a2 = x2[j]; x1[j] = a1 * cs - a2 * sn; x2[j] = a1 * sn + a2 * cs; } }
;                         x1 = x1 * osc; x2 = x2 * osc;
.LBB0_981:
	v_mov_b32_e32 v81, v152
	s_and_b64 vcc, exec, s[8:9]
	v_add3_u32 v84, v81, s24, 48
	v_mov_b32_e32 v81, v80
	s_cbranch_vccnz .LBB0_985
	v_mov_b32_e32 v82, v80
	v_mov_b32_e32 v83, v80
	v_pk_mul_f32 v[86:87], v[78:79], v[82:83]
	v_pk_mul_f32 v[88:89], v[76:77], v[80:81]
	v_mov_b64_e32 v[76:77], v[226:227]
	v_mov_b64_e32 v[78:79], v[228:229]
	v_pk_mul_f32 v[74:75], v[74:75], v[82:83]
	v_pk_mul_f32 v[82:83], v[72:73], v[80:81]
	s_and_b64 vcc, exec, s[6:7]
	v_pk_mul_f32 v[78:79], v[86:87], v[78:79]
	v_pk_mul_f32 v[76:77], v[88:89], v[76:77]
	v_mov_b64_e32 v[86:87], v[230:231]
	v_mov_b64_e32 v[88:89], v[232:233]
	v_pk_mul_f32 v[72:73], v[74:75], v[88:89]
	v_pk_mul_f32 v[82:83], v[82:83], v[86:87]
	s_cbranch_vccnz .LBB0_984
	v_bfe_u32 v74, v84, 6, 5
	v_cvt_f32_ubyte0_e32 v85, v74
	v_mul_f32_e32 v74, v155, v85
	v_rndne_f32_e32 v74, v74
	v_fma_f32 v75, v155, v85, -v74
	v_sin_f32_e32 v74, v75
	v_cos_f32_e32 v86, v75
	v_mul_f32_e32 v75, v156, v85
	v_rndne_f32_e32 v75, v75
	v_mul_f32_e32 v88, v157, v85
	v_mul_f32_e32 v94, v158, v85
	v_fma_f32 v87, v156, v85, -v75
	v_rndne_f32_e32 v88, v88
	v_rndne_f32_e32 v94, v94
	v_sin_f32_e32 v75, v87
	v_fma_f32 v88, v157, v85, -v88
	v_fma_f32 v85, v158, v85, -v94
	v_cos_f32_e32 v87, v87
	v_cos_f32_e32 v91, v88
	v_sin_f32_e32 v93, v88
	v_sin_f32_e32 v95, v85
	v_cos_f32_e32 v94, v85
	v_pk_mul_f32 v[88:89], v[74:75], v[82:83]
	v_pk_mul_f32 v[82:83], v[86:87], v[82:83]
	v_mul_f32_e32 v92, v93, v72
	v_mul_f32_e32 v100, v91, v72
	v_mov_b32_e32 v72, v79
	v_pk_fma_f32 v[86:87], v[86:87], v[76:77], v[88:89] neg_lo:[0,0,1] neg_hi:[0,0,1]
	v_mov_b32_e32 v88, v95
	v_mov_b32_e32 v89, v94
	v_mul_f32_e32 v90, v91, v78
	v_mul_f32_e32 v98, v93, v78
	v_pk_mul_f32 v[78:79], v[94:95], v[72:73]
	v_pk_mul_f32 v[72:73], v[88:89], v[72:73]
	v_mov_b32_e32 v91, v78
	v_mov_b32_e32 v93, v79
	v_mov_b32_e32 v99, v72
	v_mov_b32_e32 v101, v73
	v_pk_add_f32 v[78:79], v[90:91], v[92:93] neg_lo:[0,1] neg_hi:[0,1]
	v_pk_fma_f32 v[82:83], v[74:75], v[76:77], v[82:83]
	v_pk_add_f32 v[72:73], v[98:99], v[100:101]
	v_mov_b32_e32 v76, v86
	v_mov_b32_e32 v77, v87

; __device__ __forceinline__ unsigned cvt_pk_bf16(float lo, float hi) { unsigned r; asm volatile("v_cvt_pk_bf16_f32 %0, %1, %2" : "=v"(r) : "v"(lo), "v"(hi)); return r; }
;     __device__ __forceinline__ void operator()(const f32x4 (&acc)[2][2][4][2], const Unit& u, int wr, int wc, int fr, int fq) const {
;     ...
; #pragma unroll
;                 for (int n = 0; n < 2; ++n) {
;                     f32x4 x1 = acc[ai][0][m][n], x2 = acc[ai][1][m][n];
;                     if (!isv) {
;                         x1 = x1 * rstd * *(const f32x4*)(gp + 32 * n + 4 * fq); x2 = x2 * rstd * *(const f32x4*)(gp + 32 * n + 4 * fq + 16);
;                         if (lat) { const float pos = n ? (float)(t & 63) : (float)(t >> 6);
; #pragma unroll
;                             for (int j = 0; j < 4; ++j) { float tr = pos * inv[j]; tr -= rintf(tr);
;                                 const float sn = __builtin_amdgcn_sinf(tr), cs = __builtin_amdgcn_cosf(tr);
;                                 const float a1 = x1[j], a2 = x2[j]; x1[j] = a1 * cs - a2 * sn; x2[j] = a1 * sn + a2 * cs; } }
;                         x1 = x1 * osc; x2 = x2 * osc;
;                     }
;                     u32x2 a1, a2; a1.x = cvt_pk_bf16(x1[0], x1[1]); a1.y = cvt_pk_bf16(x1[2], x1[3]); a2.x = cvt_pk_bf16(x2[0], x2[1]); a2.y = cvt_pk_bf16(x2[2], x2[3]);
;                     *(u32x2*)(base + off + n * 64) = a1; *(u32x2*)(base + off + n * 64 + 32) = a2; }
.LBB0_985:
	v_add_u32_e32 v82, 0x24000, v144
	s_and_b64 vcc, exec, s[8:9]
	v_cvt_pk_bf16_f32 v76, v76, v77
	v_cvt_pk_bf16_f32 v77, v78, v79
	v_cvt_pk_bf16_f32 v72, v72, v73
	v_cvt_pk_bf16_f32 v73, v74, v75
	global_store_dwordx2 v82, v[76:77], s[60:61]
	global_store_dwordx2 v82, v[72:73], s[60:61] offset:32
	s_cbranch_vccnz .LBB0_989
	v_mov_b32_e32 v72, v80
	v_mov_b32_e32 v73, v80
	v_pk_mul_f32 v[74:75], v[70:71], v[72:73]
	v_pk_mul_f32 v[76:77], v[68:69], v[80:81]
	v_mov_b64_e32 v[68:69], v[234:235]
	v_mov_b64_e32 v[70:71], v[236:237]
	v_pk_mul_f32 v[66:67], v[66:67], v[72:73]
	s_and_b64 vcc, exec, s[6:7]
	v_pk_mul_f32 v[70:71], v[74:75], v[70:71]
	v_mov_b64_e32 v[72:73], v[238:239]
	v_mov_b64_e32 v[74:75], v[240:241]
	v_pk_mul_f32 v[68:69], v[76:77], v[68:69]
	v_pk_mul_f32 v[76:77], v[64:65], v[80:81]
	v_pk_mul_f32 v[64:65], v[66:67], v[74:75]
	v_pk_mul_f32 v[72:73], v[76:77], v[72:73]
	s_cbranch_vccnz .LBB0_988
	v_and_b32_e32 v66, 63, v84
	v_cvt_f32_ubyte0_e32 v79, v66
	v_mul_f32_e32 v66, v155, v79
	v_rndne_f32_e32 v66, v66
	v_fma_f32 v67, v155, v79, -v66
	v_sin_f32_e32 v66, v67
	v_cos_f32_e32 v74, v67
	v_mul_f32_e32 v67, v156, v79
	v_rndne_f32_e32 v67, v67
	v_mul_f32_e32 v76, v157, v79
	v_mul_f32_e32 v84, v158, v79
	v_fma_f32 v75, v156, v79, -v67
	v_rndne_f32_e32 v76, v76
	v_rndne_f32_e32 v84, v84
	v_sin_f32_e32 v67, v75
	v_fma_f32 v76, v157, v79, -v76
	v_fma_f32 v79, v158, v79, -v84
	v_cos_f32_e32 v75, v75
	v_cos_f32_e32 v81, v76
	v_sin_f32_e32 v83, v76
	v_sin_f32_e32 v85, v79
	v_cos_f32_e32 v84, v79
	v_pk_mul_f32 v[76:77], v[66:67], v[72:73]
	v_pk_mul_f32 v[72:73], v[74:75], v[72:73]
	v_mul_f32_e32 v80, v83, v64
	v_mul_f32_e32 v88, v81, v64
	v_mov_b32_e32 v64, v71
	v_pk_fma_f32 v[74:75], v[74:75], v[68:69], v[76:77] neg_lo:[0,0,1] neg_hi:[0,0,1]
	v_mov_b32_e32 v76, v85
	v_mov_b32_e32 v77, v84
	v_mul_f32_e32 v78, v81, v70
	v_mul_f32_e32 v86, v83, v70
	v_pk_mul_f32 v[70:71], v[84:85], v[64:65]
	v_pk_mul_f32 v[64:65], v[76:77], v[64:65]
	v_mov_b32_e32 v79, v70
	v_mov_b32_e32 v81, v71
	v_mov_b32_e32 v87, v64
	v_mov_b32_e32 v89, v65
	v_pk_add_f32 v[70:71], v[78:79], v[80:81] neg_lo:[0,1] neg_hi:[0,1]
	v_pk_fma_f32 v[72:73], v[66:67], v[68:69], v[72:73]
	v_pk_add_f32 v[64:65], v[86:87], v[88:89]
	v_mov_b32_e32 v68, v74
	v_mov_b32_e32 v69, v75

;     __device__ __forceinline__ void operator()(const f32x4 (&acc)[2][2][4][2], const Unit& u, int wr, int wc, int fr, int fq) const {
;     ...
;                 int frl = fr; asm volatile("" : "+v"(frl));
;                 const int t = (u.pm * BM + ai * HALF + wr * 64 + m * 16 + frl) & (SEQ - 1);
; #pragma unroll
;                 for (int n = 0; n < 2; ++n) {
;                     f32x4 x1 = acc[ai][0][m][n], x2 = acc[ai][1][m][n];
;                     if (!isv) {
;                         x1 = x1 * rstd * *(const f32x4*)(gp + 32 * n + 4 * fq); x2 = x2 * rstd * *(const f32x4*)(gp + 32 * n + 4 * fq + 16);
;                         if (lat) { const float pos = n ? (float)(t & 63) : (float)(t >> 6);
; #pragma unroll
;                             for (int j = 0; j < 4; ++j) { float tr = pos * inv[j]; tr -= rintf(tr);
;                                 const float sn = __builtin_amdgcn_sinf(tr), cs = __builtin_amdgcn_cosf(tr);
;                                 const float a1 = x1[j], a2 = x2[j]; x1[j] = a1 * cs - a2 * sn; x2[j] = a1 * sn + a2 * cs; } }
;                         x1 = x1 * osc; x2 = x2 * osc;
.LBB0_991:
	v_mov_b32_e32 v68, v152
	s_and_b64 vcc, exec, s[8:9]
	v_mov_b32_e32 v65, v64
	s_cbranch_vccnz .LBB0_995
	v_mov_b32_e32 v66, v64
	v_mov_b32_e32 v67, v64
	v_pk_mul_f32 v[70:71], v[62:63], v[66:67]
	v_pk_mul_f32 v[72:73], v[60:61], v[64:65]
	v_mov_b64_e32 v[60:61], v[226:227]
	v_mov_b64_e32 v[62:63], v[228:229]
	v_pk_mul_f32 v[58:59], v[58:59], v[66:67]
	v_pk_mul_f32 v[66:67], v[56:57], v[64:65]
	s_and_b64 vcc, exec, s[6:7]
	v_pk_mul_f32 v[62:63], v[70:71], v[62:63]
	v_pk_mul_f32 v[60:61], v[72:73], v[60:61]
	v_mov_b64_e32 v[70:71], v[230:231]
	v_mov_b64_e32 v[72:73], v[232:233]
	v_pk_mul_f32 v[56:57], v[58:59], v[72:73]
	v_pk_mul_f32 v[66:67], v[66:67], v[70:71]
	s_cbranch_vccnz .LBB0_994
	s_add_i32 s0, s24, 0x80
	v_add_u32_e32 v58, s0, v68
	v_bfe_u32 v58, v58, 6, 5
	v_cvt_f32_ubyte0_e32 v69, v58
	v_mul_f32_e32 v58, v155, v69
	v_rndne_f32_e32 v58, v58
	v_fma_f32 v59, v155, v69, -v58
	v_sin_f32_e32 v58, v59
	v_cos_f32_e32 v70, v59
	v_mul_f32_e32 v59, v156, v69
	v_rndne_f32_e32 v59, v59
	v_mul_f32_e32 v72, v157, v69
	v_mul_f32_e32 v78, v158, v69
	v_fma_f32 v71, v156, v69, -v59
	v_rndne_f32_e32 v72, v72
	v_rndne_f32_e32 v78, v78
	v_sin_f32_e32 v59, v71
	v_fma_f32 v72, v157, v69, -v72
	v_fma_f32 v69, v158, v69, -v78
	v_cos_f32_e32 v71, v71
	v_cos_f32_e32 v75, v72
	v_sin_f32_e32 v77, v72
	v_sin_f32_e32 v79, v69
	v_cos_f32_e32 v78, v69
	v_pk_mul_f32 v[72:73], v[58:59], v[66:67]
	v_pk_mul_f32 v[66:67], v[70:71], v[66:67]
	v_mul_f32_e32 v76, v77, v56
	v_mul_f32_e32 v82, v75, v56
	v_mov_b32_e32 v56, v63
	v_pk_fma_f32 v[70:71], v[70:71], v[60:61], v[72:73] neg_lo:[0,0,1] neg_hi:[0,0,1]
	v_mov_b32_e32 v72, v79
	v_mov_b32_e32 v73, v78
	v_mul_f32_e32 v74, v75, v62
	v_mul_f32_e32 v80, v77, v62
	v_pk_mul_f32 v[62:63], v[78:79], v[56:57]
	v_pk_mul_f32 v[56:57], v[72:73], v[56:57]
	v_mov_b32_e32 v75, v62
	v_mov_b32_e32 v77, v63
	v_mov_b32_e32 v81, v56
	v_mov_b32_e32 v83, v57
	v_pk_add_f32 v[62:63], v[74:75], v[76:77] neg_lo:[0,1] neg_hi:[0,1]
	v_pk_fma_f32 v[66:67], v[58:59], v[60:61], v[66:67]
	v_pk_add_f32 v[56:57], v[80:81], v[82:83]
	v_mov_b32_e32 v60, v70
	v_mov_b32_e32 v61, v71

; __device__ __forceinline__ unsigned cvt_pk_bf16(float lo, float hi) { unsigned r; asm volatile("v_cvt_pk_bf16_f32 %0, %1, %2" : "=v"(r) : "v"(lo), "v"(hi)); return r; }
;     __device__ __forceinline__ void operator()(const f32x4 (&acc)[2][2][4][2], const Unit& u, int wr, int wc, int fr, int fq) const {
;     ...
; #pragma unroll
;                 for (int n = 0; n < 2; ++n) {
;                     f32x4 x1 = acc[ai][0][m][n], x2 = acc[ai][1][m][n];
;                     if (!isv) {
;                         x1 = x1 * rstd * *(const f32x4*)(gp + 32 * n + 4 * fq); x2 = x2 * rstd * *(const f32x4*)(gp + 32 * n + 4 * fq + 16);
;                         if (lat) { const float pos = n ? (float)(t & 63) : (float)(t >> 6);
; #pragma unroll
;                             for (int j = 0; j < 4; ++j) { float tr = pos * inv[j]; tr -= rintf(tr);
;                                 const float sn = __builtin_amdgcn_sinf(tr), cs = __builtin_amdgcn_cosf(tr);
;                                 const float a1 = x1[j], a2 = x2[j]; x1[j] = a1 * cs - a2 * sn; x2[j] = a1 * sn + a2 * cs; } }
;                         x1 = x1 * osc; x2 = x2 * osc;
;                     }
;                     u32x2 a1, a2; a1.x = cvt_pk_bf16(x1[0], x1[1]); a1.y = cvt_pk_bf16(x1[2], x1[3]); a2.x = cvt_pk_bf16(x2[0], x2[1]); a2.y = cvt_pk_bf16(x2[2], x2[3]);
;                     *(u32x2*)(base + off + n * 64) = a1; *(u32x2*)(base + off + n * 64 + 32) = a2; }
.LBB0_995:
	v_add_u32_e32 v66, 0x60000, v144
	s_and_b64 vcc, exec, s[8:9]
	v_cvt_pk_bf16_f32 v60, v60, v61
	v_cvt_pk_bf16_f32 v61, v62, v63
	v_cvt_pk_bf16_f32 v56, v56, v57
	v_cvt_pk_bf16_f32 v57, v58, v59
	global_store_dwordx2 v66, v[60:61], s[60:61]
	global_store_dwordx2 v66, v[56:57], s[60:61] offset:32
	s_cbranch_vccnz .LBB0_999
	v_mov_b32_e32 v56, v64
	v_mov_b32_e32 v57, v64
	v_pk_mul_f32 v[58:59], v[54:55], v[56:57]
	v_pk_mul_f32 v[60:61], v[52:53], v[64:65]
	v_mov_b64_e32 v[52:53], v[234:235]
	v_mov_b64_e32 v[54:55], v[236:237]
	v_pk_mul_f32 v[50:51], v[50:51], v[56:57]
	s_and_b64 vcc, exec, s[6:7]
	v_pk_mul_f32 v[54:55], v[58:59], v[54:55]
	v_mov_b64_e32 v[56:57], v[238:239]
	v_mov_b64_e32 v[58:59], v[240:241]
	v_pk_mul_f32 v[52:53], v[60:61], v[52:53]
	v_pk_mul_f32 v[60:61], v[48:49], v[64:65]
	v_pk_mul_f32 v[48:49], v[50:51], v[58:59]
	v_pk_mul_f32 v[56:57], v[60:61], v[56:57]
	s_cbranch_vccnz .LBB0_998
	v_and_b32_e32 v50, 63, v68
	v_cvt_f32_ubyte0_e32 v63, v50
	v_mul_f32_e32 v50, v155, v63
	v_rndne_f32_e32 v50, v50
	v_fma_f32 v51, v155, v63, -v50
	v_sin_f32_e32 v50, v51
	v_cos_f32_e32 v58, v51
	v_mul_f32_e32 v51, v156, v63
	v_rndne_f32_e32 v51, v51
	v_mul_f32_e32 v60, v157, v63
	v_mul_f32_e32 v68, v158, v63
	v_fma_f32 v59, v156, v63, -v51
	v_rndne_f32_e32 v60, v60
	v_rndne_f32_e32 v68, v68
	v_sin_f32_e32 v51, v59
	v_fma_f32 v60, v157, v63, -v60
	v_fma_f32 v63, v158, v63, -v68
	v_cos_f32_e32 v59, v59
	v_cos_f32_e32 v65, v60
	v_sin_f32_e32 v67, v60
	v_sin_f32_e32 v69, v63
	v_cos_f32_e32 v68, v63
	v_pk_mul_f32 v[60:61], v[50:51], v[56:57]
	v_pk_mul_f32 v[56:57], v[58:59], v[56:57]
	v_mul_f32_e32 v64, v67, v48
	v_mul_f32_e32 v72, v65, v48
	v_mov_b32_e32 v48, v55
	v_pk_fma_f32 v[58:59], v[58:59], v[52:53], v[60:61] neg_lo:[0,0,1] neg_hi:[0,0,1]
	v_mov_b32_e32 v60, v69
	v_mov_b32_e32 v61, v68
	v_mul_f32_e32 v62, v65, v54
	v_mul_f32_e32 v70, v67, v54
	v_pk_mul_f32 v[54:55], v[68:69], v[48:49]
	v_pk_mul_f32 v[48:49], v[60:61], v[48:49]
	v_mov_b32_e32 v63, v54
	v_mov_b32_e32 v65, v55
	v_mov_b32_e32 v71, v48
	v_mov_b32_e32 v73, v49
	v_pk_add_f32 v[54:55], v[62:63], v[64:65] neg_lo:[0,1] neg_hi:[0,1]
	v_pk_fma_f32 v[56:57], v[50:51], v[52:53], v[56:57]
	v_pk_add_f32 v[48:49], v[70:71], v[72:73]
	v_mov_b32_e32 v52, v58
	v_mov_b32_e32 v53, v59

;     __device__ __forceinline__ void operator()(const f32x4 (&acc)[2][2][4][2], const Unit& u, int wr, int wc, int fr, int fq) const {
;     ...
;                 int frl = fr; asm volatile("" : "+v"(frl));
;                 const int t = (u.pm * BM + ai * HALF + wr * 64 + m * 16 + frl) & (SEQ - 1);
; #pragma unroll
;                 for (int n = 0; n < 2; ++n) {
;                     f32x4 x1 = acc[ai][0][m][n], x2 = acc[ai][1][m][n];
;                     if (!isv) {
;                         x1 = x1 * rstd * *(const f32x4*)(gp + 32 * n + 4 * fq); x2 = x2 * rstd * *(const f32x4*)(gp + 32 * n + 4 * fq + 16);
;                         if (lat) { const float pos = n ? (float)(t & 63) : (float)(t >> 6);
; #pragma unroll
;                             for (int j = 0; j < 4; ++j) { float tr = pos * inv[j]; tr -= rintf(tr);
;                                 const float sn = __builtin_amdgcn_sinf(tr), cs = __builtin_amdgcn_cosf(tr);
;                                 const float a1 = x1[j], a2 = x2[j]; x1[j] = a1 * cs - a2 * sn; x2[j] = a1 * sn + a2 * cs; } }
;                         x1 = x1 * osc; x2 = x2 * osc;
.LBB0_1001:
	v_mov_b32_e32 v49, v152
	s_add_i32 s0, s24, 0x90
	v_add_u32_e32 v52, s0, v49
	s_and_b64 vcc, exec, s[8:9]
	v_mov_b32_e32 v49, v48
	s_cbranch_vccnz .LBB0_1005
	v_mov_b32_e32 v50, v48
	v_mov_b32_e32 v51, v48
	v_pk_mul_f32 v[54:55], v[46:47], v[50:51]
	v_pk_mul_f32 v[56:57], v[44:45], v[48:49]
	v_mov_b64_e32 v[44:45], v[226:227]
	v_mov_b64_e32 v[46:47], v[228:229]
	v_pk_mul_f32 v[42:43], v[42:43], v[50:51]
	v_pk_mul_f32 v[50:51], v[40:41], v[48:49]
	s_and_b64 vcc, exec, s[6:7]
	v_pk_mul_f32 v[46:47], v[54:55], v[46:47]
	v_pk_mul_f32 v[44:45], v[56:57], v[44:45]
	v_mov_b64_e32 v[54:55], v[230:231]
	v_mov_b64_e32 v[56:57], v[232:233]
	v_pk_mul_f32 v[40:41], v[42:43], v[56:57]
	v_pk_mul_f32 v[50:51], v[50:51], v[54:55]
	s_cbranch_vccnz .LBB0_1004
	v_bfe_u32 v42, v52, 6, 5
	v_cvt_f32_ubyte0_e32 v53, v42
	v_mul_f32_e32 v42, v155, v53
	v_rndne_f32_e32 v42, v42
	v_fma_f32 v43, v155, v53, -v42
	v_sin_f32_e32 v42, v43
	v_cos_f32_e32 v54, v43
	v_mul_f32_e32 v43, v156, v53
	v_rndne_f32_e32 v43, v43
	v_mul_f32_e32 v56, v157, v53
	v_mul_f32_e32 v62, v158, v53
	v_fma_f32 v55, v156, v53, -v43
	v_rndne_f32_e32 v56, v56
	v_rndne_f32_e32 v62, v62
	v_sin_f32_e32 v43, v55
	v_fma_f32 v56, v157, v53, -v56
	v_fma_f32 v53, v158, v53, -v62
	v_cos_f32_e32 v55, v55
	v_cos_f32_e32 v59, v56
	v_sin_f32_e32 v61, v56
	v_sin_f32_e32 v63, v53
	v_cos_f32_e32 v62, v53
	v_pk_mul_f32 v[56:57], v[42:43], v[50:51]
	v_pk_mul_f32 v[50:51], v[54:55], v[50:51]
	v_mul_f32_e32 v60, v61, v40
	v_mul_f32_e32 v66, v59, v40
	v_mov_b32_e32 v40, v47
	v_pk_fma_f32 v[54:55], v[54:55], v[44:45], v[56:57] neg_lo:[0,0,1] neg_hi:[0,0,1]
	v_mov_b32_e32 v56, v63
	v_mov_b32_e32 v57, v62
	v_mul_f32_e32 v58, v59, v46
	v_mul_f32_e32 v64, v61, v46
	v_pk_mul_f32 v[46:47], v[62:63], v[40:41]
	v_pk_mul_f32 v[40:41], v[56:57], v[40:41]
	v_mov_b32_e32 v59, v46
	v_mov_b32_e32 v61, v47
	v_mov_b32_e32 v65, v40
	v_mov_b32_e32 v67, v41
	v_pk_add_f32 v[46:47], v[58:59], v[60:61] neg_lo:[0,1] neg_hi:[0,1]
	v_pk_fma_f32 v[50:51], v[42:43], v[44:45], v[50:51]
	v_pk_add_f32 v[40:41], v[64:65], v[66:67]
	v_mov_b32_e32 v44, v54
	v_mov_b32_e32 v45, v55

; __device__ __forceinline__ unsigned cvt_pk_bf16(float lo, float hi) { unsigned r; asm volatile("v_cvt_pk_bf16_f32 %0, %1, %2" : "=v"(r) : "v"(lo), "v"(hi)); return r; }
;     __device__ __forceinline__ void operator()(const f32x4 (&acc)[2][2][4][2], const Unit& u, int wr, int wc, int fr, int fq) const {
;     ...
; #pragma unroll
;                 for (int n = 0; n < 2; ++n) {
;                     f32x4 x1 = acc[ai][0][m][n], x2 = acc[ai][1][m][n];
;                     if (!isv) {
;                         x1 = x1 * rstd * *(const f32x4*)(gp + 32 * n + 4 * fq); x2 = x2 * rstd * *(const f32x4*)(gp + 32 * n + 4 * fq + 16);
;                         if (lat) { const float pos = n ? (float)(t & 63) : (float)(t >> 6);
; #pragma unroll
;                             for (int j = 0; j < 4; ++j) { float tr = pos * inv[j]; tr -= rintf(tr);
;                                 const float sn = __builtin_amdgcn_sinf(tr), cs = __builtin_amdgcn_cosf(tr);
;                                 const float a1 = x1[j], a2 = x2[j]; x1[j] = a1 * cs - a2 * sn; x2[j] = a1 * sn + a2 * cs; } }
;                         x1 = x1 * osc; x2 = x2 * osc;
;                     }
;                     u32x2 a1, a2; a1.x = cvt_pk_bf16(x1[0], x1[1]); a1.y = cvt_pk_bf16(x1[2], x1[3]); a2.x = cvt_pk_bf16(x2[0], x2[1]); a2.y = cvt_pk_bf16(x2[2], x2[3]);
;                     *(u32x2*)(base + off + n * 64) = a1; *(u32x2*)(base + off + n * 64 + 32) = a2; }
.LBB0_1005:
	v_add_u32_e32 v50, 0x6c000, v144
	s_and_b64 vcc, exec, s[8:9]
	v_cvt_pk_bf16_f32 v44, v44, v45
	v_cvt_pk_bf16_f32 v45, v46, v47
	v_cvt_pk_bf16_f32 v40, v40, v41
	v_cvt_pk_bf16_f32 v41, v42, v43
	global_store_dwordx2 v50, v[44:45], s[60:61]
	global_store_dwordx2 v50, v[40:41], s[60:61] offset:32
	s_cbranch_vccnz .LBB0_1009
	v_mov_b32_e32 v40, v48
	v_mov_b32_e32 v41, v48
	v_pk_mul_f32 v[42:43], v[38:39], v[40:41]
	v_pk_mul_f32 v[44:45], v[36:37], v[48:49]
	v_mov_b64_e32 v[36:37], v[234:235]
	v_mov_b64_e32 v[38:39], v[236:237]
	v_pk_mul_f32 v[34:35], v[34:35], v[40:41]
	s_and_b64 vcc, exec, s[6:7]
	v_pk_mul_f32 v[38:39], v[42:43], v[38:39]
	v_mov_b64_e32 v[40:41], v[238:239]
	v_mov_b64_e32 v[42:43], v[240:241]
	v_pk_mul_f32 v[36:37], v[44:45], v[36:37]
	v_pk_mul_f32 v[44:45], v[32:33], v[48:49]
	v_pk_mul_f32 v[32:33], v[34:35], v[42:43]
	v_pk_mul_f32 v[40:41], v[44:45], v[40:41]
	s_cbranch_vccnz .LBB0_1008
	v_and_b32_e32 v34, 63, v52
	v_cvt_f32_ubyte0_e32 v47, v34
	v_mul_f32_e32 v34, v155, v47
	v_rndne_f32_e32 v34, v34
	v_fma_f32 v35, v155, v47, -v34
	v_sin_f32_e32 v34, v35
	v_cos_f32_e32 v42, v35
	v_mul_f32_e32 v35, v156, v47
	v_rndne_f32_e32 v35, v35
	v_mul_f32_e32 v44, v157, v47
	v_mul_f32_e32 v52, v158, v47
	v_fma_f32 v43, v156, v47, -v35
	v_rndne_f32_e32 v44, v44
	v_rndne_f32_e32 v52, v52
	v_sin_f32_e32 v35, v43
	v_fma_f32 v44, v157, v47, -v44
	v_fma_f32 v47, v158, v47, -v52
	v_cos_f32_e32 v43, v43
	v_cos_f32_e32 v49, v44
	v_sin_f32_e32 v51, v44
	v_sin_f32_e32 v53, v47
	v_cos_f32_e32 v52, v47
	v_pk_mul_f32 v[44:45], v[34:35], v[40:41]
	v_pk_mul_f32 v[40:41], v[42:43], v[40:41]
	v_mul_f32_e32 v48, v51, v32
	v_mul_f32_e32 v56, v49, v32
	v_mov_b32_e32 v32, v39
	v_pk_fma_f32 v[42:43], v[42:43], v[36:37], v[44:45] neg_lo:[0,0,1] neg_hi:[0,0,1]
	v_mov_b32_e32 v44, v53
	v_mov_b32_e32 v45, v52
	v_mul_f32_e32 v46, v49, v38
	v_mul_f32_e32 v54, v51, v38
	v_pk_mul_f32 v[38:39], v[52:53], v[32:33]
	v_pk_mul_f32 v[32:33], v[44:45], v[32:33]
	v_mov_b32_e32 v47, v38
	v_mov_b32_e32 v49, v39
	v_mov_b32_e32 v55, v32
	v_mov_b32_e32 v57, v33
	v_pk_add_f32 v[38:39], v[46:47], v[48:49] neg_lo:[0,1] neg_hi:[0,1]
	v_pk_fma_f32 v[40:41], v[34:35], v[36:37], v[40:41]
	v_pk_add_f32 v[32:33], v[54:55], v[56:57]
	v_mov_b32_e32 v36, v42
	v_mov_b32_e32 v37, v43

;     __device__ __forceinline__ void operator()(const f32x4 (&acc)[2][2][4][2], const Unit& u, int wr, int wc, int fr, int fq) const {
;     ...
;                 int frl = fr; asm volatile("" : "+v"(frl));
;                 const int t = (u.pm * BM + ai * HALF + wr * 64 + m * 16 + frl) & (SEQ - 1);
; #pragma unroll
;                 for (int n = 0; n < 2; ++n) {
;                     f32x4 x1 = acc[ai][0][m][n], x2 = acc[ai][1][m][n];
;                     if (!isv) {
;                         x1 = x1 * rstd * *(const f32x4*)(gp + 32 * n + 4 * fq); x2 = x2 * rstd * *(const f32x4*)(gp + 32 * n + 4 * fq + 16);
;                         if (lat) { const float pos = n ? (float)(t & 63) : (float)(t >> 6);
; #pragma unroll
;                             for (int j = 0; j < 4; ++j) { float tr = pos * inv[j]; tr -= rintf(tr);
;                                 const float sn = __builtin_amdgcn_sinf(tr), cs = __builtin_amdgcn_cosf(tr);
;                                 const float a1 = x1[j], a2 = x2[j]; x1[j] = a1 * cs - a2 * sn; x2[j] = a1 * sn + a2 * cs; } }
;                         x1 = x1 * osc; x2 = x2 * osc;
.LBB0_1011:
	v_mov_b32_e32 v33, v152
	s_add_i32 s0, s24, 0xa0
	v_add_u32_e32 v36, s0, v33
	s_and_b64 vcc, exec, s[8:9]
	v_mov_b32_e32 v33, v32
	s_cbranch_vccnz .LBB0_1015
	v_mov_b32_e32 v34, v32
	v_mov_b32_e32 v35, v32
	v_pk_mul_f32 v[38:39], v[30:31], v[34:35]
	v_pk_mul_f32 v[40:41], v[28:29], v[32:33]
	v_mov_b64_e32 v[28:29], v[226:227]
	v_mov_b64_e32 v[30:31], v[228:229]
	v_pk_mul_f32 v[26:27], v[26:27], v[34:35]
	v_pk_mul_f32 v[34:35], v[24:25], v[32:33]
	s_and_b64 vcc, exec, s[6:7]
	v_pk_mul_f32 v[30:31], v[38:39], v[30:31]
	v_pk_mul_f32 v[28:29], v[40:41], v[28:29]
	v_mov_b64_e32 v[38:39], v[230:231]
	v_mov_b64_e32 v[40:41], v[232:233]
	v_pk_mul_f32 v[24:25], v[26:27], v[40:41]
	v_pk_mul_f32 v[34:35], v[34:35], v[38:39]
	s_cbranch_vccnz .LBB0_1014
	v_bfe_u32 v26, v36, 6, 5
	v_cvt_f32_ubyte0_e32 v37, v26
	v_mul_f32_e32 v26, v155, v37
	v_rndne_f32_e32 v26, v26
	v_fma_f32 v27, v155, v37, -v26
	v_sin_f32_e32 v26, v27
	v_cos_f32_e32 v38, v27
	v_mul_f32_e32 v27, v156, v37
	v_rndne_f32_e32 v27, v27
	v_mul_f32_e32 v40, v157, v37
	v_mul_f32_e32 v46, v158, v37
	v_fma_f32 v39, v156, v37, -v27
	v_rndne_f32_e32 v40, v40
	v_rndne_f32_e32 v46, v46
	v_sin_f32_e32 v27, v39
	v_fma_f32 v40, v157, v37, -v40
	v_fma_f32 v37, v158, v37, -v46
	v_cos_f32_e32 v39, v39
	v_cos_f32_e32 v43, v40
	v_sin_f32_e32 v45, v40
	v_sin_f32_e32 v47, v37
	v_cos_f32_e32 v46, v37
	v_pk_mul_f32 v[40:41], v[26:27], v[34:35]
	v_pk_mul_f32 v[34:35], v[38:39], v[34:35]
	v_mul_f32_e32 v44, v45, v24
	v_mul_f32_e32 v50, v43, v24
	v_mov_b32_e32 v24, v31
	v_pk_fma_f32 v[38:39], v[38:39], v[28:29], v[40:41] neg_lo:[0,0,1] neg_hi:[0,0,1]
	v_mov_b32_e32 v40, v47
	v_mov_b32_e32 v41, v46
	v_mul_f32_e32 v42, v43, v30
	v_mul_f32_e32 v48, v45, v30
	v_pk_mul_f32 v[30:31], v[46:47], v[24:25]
	v_pk_mul_f32 v[24:25], v[40:41], v[24:25]
	v_mov_b32_e32 v43, v30
	v_mov_b32_e32 v45, v31
	v_mov_b32_e32 v49, v24
	v_mov_b32_e32 v51, v25
	v_pk_add_f32 v[30:31], v[42:43], v[44:45] neg_lo:[0,1] neg_hi:[0,1]
	v_pk_fma_f32 v[34:35], v[26:27], v[28:29], v[34:35]
	v_pk_add_f32 v[24:25], v[48:49], v[50:51]
	v_mov_b32_e32 v28, v38
	v_mov_b32_e32 v29, v39

; __device__ __forceinline__ unsigned cvt_pk_bf16(float lo, float hi) { unsigned r; asm volatile("v_cvt_pk_bf16_f32 %0, %1, %2" : "=v"(r) : "v"(lo), "v"(hi)); return r; }
;     __device__ __forceinline__ void operator()(const f32x4 (&acc)[2][2][4][2], const Unit& u, int wr, int wc, int fr, int fq) const {
;     ...
; #pragma unroll
;                 for (int n = 0; n < 2; ++n) {
;                     f32x4 x1 = acc[ai][0][m][n], x2 = acc[ai][1][m][n];
;                     if (!isv) {
;                         x1 = x1 * rstd * *(const f32x4*)(gp + 32 * n + 4 * fq); x2 = x2 * rstd * *(const f32x4*)(gp + 32 * n + 4 * fq + 16);
;                         if (lat) { const float pos = n ? (float)(t & 63) : (float)(t >> 6);
; #pragma unroll
;                             for (int j = 0; j < 4; ++j) { float tr = pos * inv[j]; tr -= rintf(tr);
;                                 const float sn = __builtin_amdgcn_sinf(tr), cs = __builtin_amdgcn_cosf(tr);
;                                 const float a1 = x1[j], a2 = x2[j]; x1[j] = a1 * cs - a2 * sn; x2[j] = a1 * sn + a2 * cs; } }
;                         x1 = x1 * osc; x2 = x2 * osc;
;                     }
;                     u32x2 a1, a2; a1.x = cvt_pk_bf16(x1[0], x1[1]); a1.y = cvt_pk_bf16(x1[2], x1[3]); a2.x = cvt_pk_bf16(x2[0], x2[1]); a2.y = cvt_pk_bf16(x2[2], x2[3]);
;                     *(u32x2*)(base + off + n * 64) = a1; *(u32x2*)(base + off + n * 64 + 32) = a2; }
.LBB0_1015:
	v_add_u32_e32 v34, 0x78000, v144
	s_and_b64 vcc, exec, s[8:9]
	v_cvt_pk_bf16_f32 v28, v28, v29
	v_cvt_pk_bf16_f32 v29, v30, v31
	v_cvt_pk_bf16_f32 v24, v24, v25
	v_cvt_pk_bf16_f32 v25, v26, v27
	global_store_dwordx2 v34, v[28:29], s[60:61]
	global_store_dwordx2 v34, v[24:25], s[60:61] offset:32
	s_cbranch_vccnz .LBB0_1019
	v_mov_b32_e32 v24, v32
	v_mov_b32_e32 v25, v32
	v_pk_mul_f32 v[26:27], v[22:23], v[24:25]
	v_pk_mul_f32 v[28:29], v[20:21], v[32:33]
	v_mov_b64_e32 v[20:21], v[234:235]
	v_mov_b64_e32 v[22:23], v[236:237]
	v_pk_mul_f32 v[18:19], v[18:19], v[24:25]
	s_and_b64 vcc, exec, s[6:7]
	v_pk_mul_f32 v[22:23], v[26:27], v[22:23]
	v_mov_b64_e32 v[24:25], v[238:239]
	v_mov_b64_e32 v[26:27], v[240:241]
	v_pk_mul_f32 v[20:21], v[28:29], v[20:21]
	v_pk_mul_f32 v[28:29], v[16:17], v[32:33]
	v_pk_mul_f32 v[16:17], v[18:19], v[26:27]
	v_pk_mul_f32 v[24:25], v[28:29], v[24:25]
	s_cbranch_vccnz .LBB0_1018
	v_and_b32_e32 v18, 63, v36
	v_cvt_f32_ubyte0_e32 v31, v18
	v_mul_f32_e32 v18, v155, v31
	v_rndne_f32_e32 v18, v18
	v_fma_f32 v19, v155, v31, -v18
	v_sin_f32_e32 v18, v19
	v_cos_f32_e32 v26, v19
	v_mul_f32_e32 v19, v156, v31
	v_rndne_f32_e32 v19, v19
	v_mul_f32_e32 v28, v157, v31
	v_mul_f32_e32 v36, v158, v31
	v_fma_f32 v27, v156, v31, -v19
	v_rndne_f32_e32 v28, v28
	v_rndne_f32_e32 v36, v36
	v_sin_f32_e32 v19, v27
	v_fma_f32 v28, v157, v31, -v28
	v_fma_f32 v31, v158, v31, -v36
	v_cos_f32_e32 v27, v27
	v_cos_f32_e32 v33, v28
	v_sin_f32_e32 v35, v28
	v_sin_f32_e32 v37, v31
	v_cos_f32_e32 v36, v31
	v_pk_mul_f32 v[28:29], v[18:19], v[24:25]
	v_pk_mul_f32 v[24:25], v[26:27], v[24:25]
	v_mul_f32_e32 v32, v35, v16
	v_mul_f32_e32 v40, v33, v16
	v_mov_b32_e32 v16, v23
	v_pk_fma_f32 v[26:27], v[26:27], v[20:21], v[28:29] neg_lo:[0,0,1] neg_hi:[0,0,1]
	v_mov_b32_e32 v28, v37
	v_mov_b32_e32 v29, v36
	v_mul_f32_e32 v30, v33, v22
	v_mul_f32_e32 v38, v35, v22
	v_pk_mul_f32 v[22:23], v[36:37], v[16:17]
	v_pk_mul_f32 v[16:17], v[28:29], v[16:17]
	v_mov_b32_e32 v31, v22
	v_mov_b32_e32 v33, v23
	v_mov_b32_e32 v39, v16
	v_mov_b32_e32 v41, v17
	v_pk_add_f32 v[22:23], v[30:31], v[32:33] neg_lo:[0,1] neg_hi:[0,1]
	v_pk_fma_f32 v[24:25], v[18:19], v[20:21], v[24:25]
	v_pk_add_f32 v[16:17], v[38:39], v[40:41]
	v_mov_b32_e32 v20, v26
	v_mov_b32_e32 v21, v27

;     __device__ __forceinline__ void operator()(const f32x4 (&acc)[2][2][4][2], const Unit& u, int wr, int wc, int fr, int fq) const {
;     ...
;                 int frl = fr; asm volatile("" : "+v"(frl));
;                 const int t = (u.pm * BM + ai * HALF + wr * 64 + m * 16 + frl) & (SEQ - 1);
; #pragma unroll
;                 for (int n = 0; n < 2; ++n) {
;                     f32x4 x1 = acc[ai][0][m][n], x2 = acc[ai][1][m][n];
;                     if (!isv) {
;                         x1 = x1 * rstd * *(const f32x4*)(gp + 32 * n + 4 * fq); x2 = x2 * rstd * *(const f32x4*)(gp + 32 * n + 4 * fq + 16);
;                         if (lat) { const float pos = n ? (float)(t & 63) : (float)(t >> 6);
; #pragma unroll
;                             for (int j = 0; j < 4; ++j) { float tr = pos * inv[j]; tr -= rintf(tr);
;                                 const float sn = __builtin_amdgcn_sinf(tr), cs = __builtin_amdgcn_cosf(tr);
;                                 const float a1 = x1[j], a2 = x2[j]; x1[j] = a1 * cs - a2 * sn; x2[j] = a1 * sn + a2 * cs; } }
;                         x1 = x1 * osc; x2 = x2 * osc;
.LBB0_1021:
	v_mov_b32_e32 v17, v152
	s_addk_i32 s24, 0xb0
	v_add_u32_e32 v20, s24, v17
	s_and_b64 vcc, exec, s[8:9]
	v_mov_b32_e32 v17, v16
	s_cbranch_vccnz .LBB0_1025
	v_mov_b32_e32 v18, v16
	v_mov_b32_e32 v19, v16
	v_pk_mul_f32 v[22:23], v[14:15], v[18:19]
	v_pk_mul_f32 v[24:25], v[12:13], v[16:17]
	v_mov_b64_e32 v[12:13], v[226:227]
	v_mov_b64_e32 v[14:15], v[228:229]
	v_pk_mul_f32 v[10:11], v[10:11], v[18:19]
	v_pk_mul_f32 v[18:19], v[8:9], v[16:17]
	s_and_b64 vcc, exec, s[6:7]
	v_pk_mul_f32 v[14:15], v[22:23], v[14:15]
	v_pk_mul_f32 v[12:13], v[24:25], v[12:13]
	v_mov_b64_e32 v[22:23], v[230:231]
	v_mov_b64_e32 v[24:25], v[232:233]
	v_pk_mul_f32 v[8:9], v[10:11], v[24:25]
	v_pk_mul_f32 v[18:19], v[18:19], v[22:23]
	s_cbranch_vccnz .LBB0_1024
	v_bfe_u32 v10, v20, 6, 5
	v_cvt_f32_ubyte0_e32 v21, v10
	v_mul_f32_e32 v10, v155, v21
	v_rndne_f32_e32 v10, v10
	v_fma_f32 v11, v155, v21, -v10
	v_sin_f32_e32 v10, v11
	v_cos_f32_e32 v22, v11
	v_mul_f32_e32 v11, v156, v21
	v_rndne_f32_e32 v11, v11
	v_mul_f32_e32 v24, v157, v21
	v_mul_f32_e32 v30, v158, v21
	v_fma_f32 v23, v156, v21, -v11
	v_rndne_f32_e32 v24, v24
	v_rndne_f32_e32 v30, v30
	v_sin_f32_e32 v11, v23
	v_fma_f32 v24, v157, v21, -v24
	v_fma_f32 v21, v158, v21, -v30
	v_cos_f32_e32 v23, v23
	v_cos_f32_e32 v27, v24
	v_sin_f32_e32 v29, v24
	v_sin_f32_e32 v31, v21
	v_cos_f32_e32 v30, v21
	v_pk_mul_f32 v[24:25], v[10:11], v[18:19]
	v_pk_mul_f32 v[18:19], v[22:23], v[18:19]
	v_mul_f32_e32 v28, v29, v8
	v_mul_f32_e32 v34, v27, v8
	v_mov_b32_e32 v8, v15
	v_pk_fma_f32 v[22:23], v[22:23], v[12:13], v[24:25] neg_lo:[0,0,1] neg_hi:[0,0,1]
	v_mov_b32_e32 v24, v31
	v_mov_b32_e32 v25, v30
	v_mul_f32_e32 v26, v27, v14
	v_mul_f32_e32 v32, v29, v14
	v_pk_mul_f32 v[14:15], v[30:31], v[8:9]
	v_pk_mul_f32 v[8:9], v[24:25], v[8:9]
	v_mov_b32_e32 v27, v14
	v_mov_b32_e32 v29, v15
	v_mov_b32_e32 v33, v8
	v_mov_b32_e32 v35, v9
	v_pk_add_f32 v[14:15], v[26:27], v[28:29] neg_lo:[0,1] neg_hi:[0,1]
	v_pk_fma_f32 v[18:19], v[10:11], v[12:13], v[18:19]
	v_pk_add_f32 v[8:9], v[32:33], v[34:35]
	v_mov_b32_e32 v12, v22
	v_mov_b32_e32 v13, v23

; __device__ __forceinline__ unsigned cvt_pk_bf16(float lo, float hi) { unsigned r; asm volatile("v_cvt_pk_bf16_f32 %0, %1, %2" : "=v"(r) : "v"(lo), "v"(hi)); return r; }
;     __device__ __forceinline__ void operator()(const f32x4 (&acc)[2][2][4][2], const Unit& u, int wr, int wc, int fr, int fq) const {
;     ...
; #pragma unroll
;                 for (int n = 0; n < 2; ++n) {
;                     f32x4 x1 = acc[ai][0][m][n], x2 = acc[ai][1][m][n];
;                     if (!isv) {
;                         x1 = x1 * rstd * *(const f32x4*)(gp + 32 * n + 4 * fq); x2 = x2 * rstd * *(const f32x4*)(gp + 32 * n + 4 * fq + 16);
;                         if (lat) { const float pos = n ? (float)(t & 63) : (float)(t >> 6);
; #pragma unroll
;                             for (int j = 0; j < 4; ++j) { float tr = pos * inv[j]; tr -= rintf(tr);
;                                 const float sn = __builtin_amdgcn_sinf(tr), cs = __builtin_amdgcn_cosf(tr);
;                                 const float a1 = x1[j], a2 = x2[j]; x1[j] = a1 * cs - a2 * sn; x2[j] = a1 * sn + a2 * cs; } }
;                         x1 = x1 * osc; x2 = x2 * osc;
;                     }
;                     u32x2 a1, a2; a1.x = cvt_pk_bf16(x1[0], x1[1]); a1.y = cvt_pk_bf16(x1[2], x1[3]); a2.x = cvt_pk_bf16(x2[0], x2[1]); a2.y = cvt_pk_bf16(x2[2], x2[3]);
;                     *(u32x2*)(base + off + n * 64) = a1; *(u32x2*)(base + off + n * 64 + 32) = a2; }
.LBB0_1025:
	v_add_u32_e32 v18, 0x84000, v144
	s_and_b64 vcc, exec, s[8:9]
	v_cvt_pk_bf16_f32 v12, v12, v13
	v_cvt_pk_bf16_f32 v13, v14, v15
	v_cvt_pk_bf16_f32 v8, v8, v9
	v_cvt_pk_bf16_f32 v9, v10, v11
	global_store_dwordx2 v18, v[12:13], s[60:61]
	global_store_dwordx2 v18, v[8:9], s[60:61] offset:32
	s_cbranch_vccnz .LBB0_1029
	v_mov_b32_e32 v8, v16
	v_mov_b32_e32 v9, v16
	v_pk_mul_f32 v[10:11], v[6:7], v[8:9]
	v_pk_mul_f32 v[12:13], v[4:5], v[16:17]
	v_mov_b64_e32 v[4:5], v[234:235]
	v_mov_b64_e32 v[6:7], v[236:237]
	v_pk_mul_f32 v[2:3], v[2:3], v[8:9]
	s_and_b64 vcc, exec, s[6:7]
	v_pk_mul_f32 v[6:7], v[10:11], v[6:7]
	v_mov_b64_e32 v[8:9], v[238:239]
	v_mov_b64_e32 v[10:11], v[240:241]
	v_pk_mul_f32 v[4:5], v[12:13], v[4:5]
	v_pk_mul_f32 v[12:13], v[0:1], v[16:17]
	v_pk_mul_f32 v[0:1], v[2:3], v[10:11]
	v_pk_mul_f32 v[8:9], v[12:13], v[8:9]
	s_cbranch_vccnz .LBB0_1028
	v_and_b32_e32 v2, 63, v20
	v_cvt_f32_ubyte0_e32 v15, v2
	v_mul_f32_e32 v2, v155, v15
	v_rndne_f32_e32 v2, v2
	v_fma_f32 v3, v155, v15, -v2
	v_sin_f32_e32 v2, v3
	v_cos_f32_e32 v10, v3
	v_mul_f32_e32 v3, v156, v15
	v_rndne_f32_e32 v3, v3
	v_mul_f32_e32 v12, v157, v15
	v_mul_f32_e32 v20, v158, v15
	v_fma_f32 v11, v156, v15, -v3
	v_rndne_f32_e32 v12, v12
	v_rndne_f32_e32 v20, v20
	v_sin_f32_e32 v3, v11
	v_fma_f32 v12, v157, v15, -v12
	v_fma_f32 v15, v158, v15, -v20
	v_cos_f32_e32 v11, v11
	v_cos_f32_e32 v17, v12
	v_sin_f32_e32 v19, v12
	v_sin_f32_e32 v21, v15
	v_cos_f32_e32 v20, v15
	v_pk_mul_f32 v[12:13], v[2:3], v[8:9]
	v_pk_mul_f32 v[8:9], v[10:11], v[8:9]
	v_mul_f32_e32 v16, v19, v0
	v_mul_f32_e32 v24, v17, v0
	v_mov_b32_e32 v0, v7
	v_pk_fma_f32 v[10:11], v[10:11], v[4:5], v[12:13] neg_lo:[0,0,1] neg_hi:[0,0,1]
	v_mov_b32_e32 v12, v21
	v_mov_b32_e32 v13, v20
	v_mul_f32_e32 v14, v17, v6
	v_mul_f32_e32 v22, v19, v6
	v_pk_mul_f32 v[6:7], v[20:21], v[0:1]
	v_pk_mul_f32 v[0:1], v[12:13], v[0:1]
	v_mov_b32_e32 v15, v6
	v_mov_b32_e32 v17, v7
	v_mov_b32_e32 v23, v0
	v_mov_b32_e32 v25, v1
	v_pk_add_f32 v[6:7], v[14:15], v[16:17] neg_lo:[0,1] neg_hi:[0,1]
	v_pk_fma_f32 v[8:9], v[2:3], v[4:5], v[8:9]
	v_pk_add_f32 v[0:1], v[22:23], v[24:25]
	v_mov_b32_e32 v4, v10
	v_mov_b32_e32 v5, v11
